# v21: v20 + accumulate-chain order also in the peeled first iterations and the two rotating-register loop segments of GEMM copy 2
# speedup vs baseline: 1.0006x; 1.0006x over previous
.LBB0_730:
	s_or_b32 s20, s90, 1
	s_add_i32 s90, s90, 2
	s_mov_b32 s91, s21
	ds_read_b128 v[142:145], v137
	ds_read_b128 v[146:149], v137 offset:1024
	ds_read_b128 v[150:153], v137 offset:2048
	ds_read_b128 v[154:157], v137 offset:3072
	ds_read_b128 v[158:161], v138
	ds_read_b128 v[162:165], v138 offset:1024
	ds_read_b128 v[166:169], v138 offset:2048
	ds_read_b128 v[172:175], v138 offset:3072
	s_lshl_b64 s[96:97], s[20:21], 7
	s_lshl_b64 s[2:3], s[90:91], 7
	s_add_u32 s20, s78, s2
	s_addc_u32 s73, s79, s3
	s_and_b64 s[12:13], s[92:93], exec
	s_cselect_b32 s95, s73, s87
	s_cselect_b32 s94, s20, s86
	s_add_u32 s12, s76, s2
	s_addc_u32 s13, s77, s3
	s_and_b64 s[2:3], s[92:93], exec
	s_cselect_b32 s93, s13, s89
	s_cselect_b32 s92, s12, s88
	s_add_u32 s2, s94, 0x80
	s_addc_u32 s3, s95, 0
	s_add_u32 s12, s92, 0x80
	s_addc_u32 s13, s93, 0
	ds_read_b128 v[176:179], v136
	ds_read_b128 v[180:183], v136 offset:1024
	ds_read_b128 v[184:187], v136 offset:2048
	ds_read_b128 v[188:191], v136 offset:3072
	ds_read_b128 v[196:199], v136 offset:4096
	ds_read_b128 v[200:203], v136 offset:5120
	ds_read_b128 v[204:207], v136 offset:6144
	ds_read_b128 v[208:211], v136 offset:7168
	s_add_u32 s96, s59, s96
	s_addc_u32 s97, s38, s97
	s_add_i32 m0, s43, 0xc000
	s_nop 0
	global_load_lds_dwordx4 v134, s[96:97]
	s_nop 0
	s_add_i32 m0, s43, 0xe000
	s_nop 0
	global_load_lds_dwordx4 v135, s[96:97]
	s_waitcnt vmcnt(8)
	s_waitcnt lgkmcnt(0)
	s_setprio 1
	s_barrier
	v_mfma_f32_16x16x32_bf16 v[70:73], v[142:145], v[176:179], v[70:73]
	v_mfma_f32_16x16x32_bf16 v[70:73], v[146:149], v[180:183], v[70:73]
	v_mfma_f32_16x16x32_bf16 v[74:77], v[142:145], v[184:187], v[74:77]
	v_mfma_f32_16x16x32_bf16 v[74:77], v[146:149], v[188:191], v[74:77]
	v_mfma_f32_16x16x32_bf16 v[78:81], v[142:145], v[196:199], v[78:81]
	v_mfma_f32_16x16x32_bf16 v[78:81], v[146:149], v[200:203], v[78:81]
	v_mfma_f32_16x16x32_bf16 v[82:85], v[142:145], v[204:207], v[82:85]
	v_mfma_f32_16x16x32_bf16 v[82:85], v[146:149], v[208:211], v[82:85]
	v_mfma_f32_16x16x32_bf16 v[86:89], v[150:153], v[176:179], v[86:89]
	v_mfma_f32_16x16x32_bf16 v[86:89], v[154:157], v[180:183], v[86:89]
	v_mfma_f32_16x16x32_bf16 v[90:93], v[150:153], v[184:187], v[90:93]
	v_mfma_f32_16x16x32_bf16 v[90:93], v[154:157], v[188:191], v[90:93]
	v_mfma_f32_16x16x32_bf16 v[94:97], v[150:153], v[196:199], v[94:97]
	v_mfma_f32_16x16x32_bf16 v[94:97], v[154:157], v[200:203], v[94:97]
	v_mfma_f32_16x16x32_bf16 v[98:101], v[150:153], v[204:207], v[98:101]
	v_mfma_f32_16x16x32_bf16 v[98:101], v[154:157], v[208:211], v[98:101]
	v_mfma_f32_16x16x32_bf16 v[102:105], v[158:161], v[176:179], v[102:105]
	v_mfma_f32_16x16x32_bf16 v[102:105], v[162:165], v[180:183], v[102:105]
	v_mfma_f32_16x16x32_bf16 v[106:109], v[158:161], v[184:187], v[106:109]
	v_mfma_f32_16x16x32_bf16 v[106:109], v[162:165], v[188:191], v[106:109]
	v_mfma_f32_16x16x32_bf16 v[110:113], v[158:161], v[196:199], v[110:113]
	v_mfma_f32_16x16x32_bf16 v[110:113], v[162:165], v[200:203], v[110:113]
	v_mfma_f32_16x16x32_bf16 v[114:117], v[158:161], v[204:207], v[114:117]
	v_mfma_f32_16x16x32_bf16 v[114:117], v[162:165], v[208:211], v[114:117]
	v_mfma_f32_16x16x32_bf16 v[118:121], v[166:169], v[176:179], v[118:121]
	v_mfma_f32_16x16x32_bf16 v[118:121], v[172:175], v[180:183], v[118:121]
	v_mfma_f32_16x16x32_bf16 v[122:125], v[166:169], v[184:187], v[122:125]
	v_mfma_f32_16x16x32_bf16 v[122:125], v[172:175], v[188:191], v[122:125]
	v_mfma_f32_16x16x32_bf16 v[126:129], v[166:169], v[196:199], v[126:129]
	v_mfma_f32_16x16x32_bf16 v[126:129], v[172:175], v[200:203], v[126:129]
	v_mfma_f32_16x16x32_bf16 v[130:133], v[166:169], v[204:207], v[130:133]
	v_mfma_f32_16x16x32_bf16 v[130:133], v[172:175], v[208:211], v[130:133]
	s_barrier
	s_setprio 0
	ds_read_b128 v[176:179], v136 offset:16384
	ds_read_b128 v[180:183], v136 offset:17408
	ds_read_b128 v[184:187], v136 offset:18432
	ds_read_b128 v[188:191], v136 offset:19456
	ds_read_b128 v[196:199], v136 offset:20480
	ds_read_b128 v[200:203], v136 offset:21504
	ds_read_b128 v[204:207], v136 offset:22528
	ds_read_b128 v[208:211], v136 offset:23552
	s_add_i32 m0, s43, 0x10000
	s_nop 0
	global_load_lds_dwordx4 v134, s[92:93]
	s_nop 0
	s_add_i32 m0, s43, 0x12000
	s_nop 0
	global_load_lds_dwordx4 v135, s[92:93]
	s_add_u32 s92, s92, s16
	s_addc_u32 s93, s93, 0
	s_add_i32 m0, s43, 0x14000
	s_nop 0
	global_load_lds_dwordx4 v134, s[92:93]
	s_nop 0
	s_add_i32 m0, s43, 0x16000
	s_nop 0
	global_load_lds_dwordx4 v135, s[92:93]
	s_nop 0
	s_add_i32 m0, s43, 0
	s_nop 0
	global_load_lds_dwordx4 v134, s[94:95]
	s_nop 0
	s_add_i32 m0, s43, 0x2000
	s_nop 0
	global_load_lds_dwordx4 v135, s[94:95]
	s_waitcnt vmcnt(8)
	s_waitcnt lgkmcnt(0)
	s_setprio 1
	s_barrier
	v_mfma_f32_16x16x32_bf16 v[4:7], v[142:145], v[176:179], v[6:9]
	v_mfma_f32_16x16x32_bf16 v[4:7], v[146:149], v[180:183], v[4:7]
	v_mfma_f32_16x16x32_bf16 v[22:25], v[150:153], v[176:179], v[22:25]
	v_mfma_f32_16x16x32_bf16 v[22:25], v[154:157], v[180:183], v[22:25]
	v_mfma_f32_16x16x32_bf16 v[8:11], v[142:145], v[184:187], v[10:13]
	v_mfma_f32_16x16x32_bf16 v[10:13], v[146:149], v[188:191], v[8:11]
	v_mfma_f32_16x16x32_bf16 v[26:29], v[150:153], v[184:187], v[26:29]
	v_mfma_f32_16x16x32_bf16 v[26:29], v[154:157], v[188:191], v[26:29]
	v_mfma_f32_16x16x32_bf16 v[14:17], v[142:145], v[196:199], v[14:17]
	v_mfma_f32_16x16x32_bf16 v[14:17], v[146:149], v[200:203], v[14:17]
	v_mfma_f32_16x16x32_bf16 v[30:33], v[150:153], v[196:199], v[30:33]
	v_mfma_f32_16x16x32_bf16 v[30:33], v[154:157], v[200:203], v[30:33]
	v_mfma_f32_16x16x32_bf16 v[18:21], v[142:145], v[204:207], v[18:21]
	v_mfma_f32_16x16x32_bf16 v[18:21], v[146:149], v[208:211], v[18:21]
	v_mfma_f32_16x16x32_bf16 v[34:37], v[150:153], v[204:207], v[34:37]
	v_mfma_f32_16x16x32_bf16 v[34:37], v[154:157], v[208:211], v[34:37]
	v_mfma_f32_16x16x32_bf16 v[38:41], v[158:161], v[176:179], v[38:41]
	v_mfma_f32_16x16x32_bf16 v[38:41], v[162:165], v[180:183], v[38:41]
	v_mfma_f32_16x16x32_bf16 v[54:57], v[166:169], v[176:179], v[54:57]
	v_mfma_f32_16x16x32_bf16 v[54:57], v[172:175], v[180:183], v[54:57]
	v_mfma_f32_16x16x32_bf16 v[42:45], v[158:161], v[184:187], v[42:45]
	v_mfma_f32_16x16x32_bf16 v[42:45], v[162:165], v[188:191], v[42:45]
	v_mfma_f32_16x16x32_bf16 v[58:61], v[166:169], v[184:187], v[58:61]
	v_mfma_f32_16x16x32_bf16 v[58:61], v[172:175], v[188:191], v[58:61]
	v_mfma_f32_16x16x32_bf16 v[46:49], v[158:161], v[196:199], v[46:49]
	v_mfma_f32_16x16x32_bf16 v[46:49], v[162:165], v[200:203], v[46:49]
	v_mfma_f32_16x16x32_bf16 v[62:65], v[166:169], v[196:199], v[62:65]
	v_mfma_f32_16x16x32_bf16 v[62:65], v[172:175], v[200:203], v[62:65]
	v_mfma_f32_16x16x32_bf16 v[50:53], v[158:161], v[204:207], v[50:53]
	v_mfma_f32_16x16x32_bf16 v[50:53], v[162:165], v[208:211], v[50:53]
	v_mfma_f32_16x16x32_bf16 v[66:69], v[166:169], v[204:207], v[66:69]
	v_mfma_f32_16x16x32_bf16 v[66:69], v[172:175], v[208:211], v[66:69]
	s_barrier
	s_setprio 0
	ds_read_b128 v[142:145], v139
	ds_read_b128 v[146:149], v139 offset:1024
	ds_read_b128 v[150:153], v139 offset:2048
	ds_read_b128 v[154:157], v139 offset:3072
	ds_read_b128 v[158:161], v140
	ds_read_b128 v[162:165], v140 offset:1024
	ds_read_b128 v[166:169], v140 offset:2048
	ds_read_b128 v[172:175], v140 offset:3072
	ds_read_b128 v[176:179], v136 offset:32768
	ds_read_b128 v[180:183], v136 offset:33792
	ds_read_b128 v[184:187], v136 offset:34816
	ds_read_b128 v[188:191], v136 offset:35840
	ds_read_b128 v[196:199], v136 offset:36864
	ds_read_b128 v[200:203], v136 offset:37888
	ds_read_b128 v[204:207], v136 offset:38912
	ds_read_b128 v[208:211], v136 offset:39936
	s_add_u32 s92, s94, s16
	s_addc_u32 s93, s95, 0
	s_add_i32 m0, s43, 0x4000
	s_nop 0
	global_load_lds_dwordx4 v134, s[92:93]
	s_nop 0
	s_add_i32 m0, s43, 0x6000
	s_nop 0
	global_load_lds_dwordx4 v135, s[92:93]
	s_waitcnt vmcnt(8)
	s_waitcnt lgkmcnt(0)
	s_setprio 1
	s_barrier
	v_mfma_f32_16x16x32_bf16 v[70:73], v[142:145], v[176:179], v[70:73]
	v_mfma_f32_16x16x32_bf16 v[70:73], v[146:149], v[180:183], v[70:73]
	v_mfma_f32_16x16x32_bf16 v[74:77], v[142:145], v[184:187], v[74:77]
	v_mfma_f32_16x16x32_bf16 v[74:77], v[146:149], v[188:191], v[74:77]
	v_mfma_f32_16x16x32_bf16 v[78:81], v[142:145], v[196:199], v[78:81]
	v_mfma_f32_16x16x32_bf16 v[78:81], v[146:149], v[200:203], v[78:81]
	v_mfma_f32_16x16x32_bf16 v[82:85], v[142:145], v[204:207], v[82:85]
	v_mfma_f32_16x16x32_bf16 v[82:85], v[146:149], v[208:211], v[82:85]
	v_mfma_f32_16x16x32_bf16 v[86:89], v[150:153], v[176:179], v[86:89]
	v_mfma_f32_16x16x32_bf16 v[86:89], v[154:157], v[180:183], v[86:89]
	v_mfma_f32_16x16x32_bf16 v[90:93], v[150:153], v[184:187], v[90:93]
	v_mfma_f32_16x16x32_bf16 v[90:93], v[154:157], v[188:191], v[90:93]
	v_mfma_f32_16x16x32_bf16 v[94:97], v[150:153], v[196:199], v[94:97]
	v_mfma_f32_16x16x32_bf16 v[94:97], v[154:157], v[200:203], v[94:97]
	v_mfma_f32_16x16x32_bf16 v[98:101], v[150:153], v[204:207], v[98:101]
	v_mfma_f32_16x16x32_bf16 v[98:101], v[154:157], v[208:211], v[98:101]
	v_mfma_f32_16x16x32_bf16 v[102:105], v[158:161], v[176:179], v[102:105]
	v_mfma_f32_16x16x32_bf16 v[102:105], v[162:165], v[180:183], v[102:105]
	v_mfma_f32_16x16x32_bf16 v[106:109], v[158:161], v[184:187], v[106:109]
	v_mfma_f32_16x16x32_bf16 v[106:109], v[162:165], v[188:191], v[106:109]
	v_mfma_f32_16x16x32_bf16 v[110:113], v[158:161], v[196:199], v[110:113]
	v_mfma_f32_16x16x32_bf16 v[110:113], v[162:165], v[200:203], v[110:113]
	v_mfma_f32_16x16x32_bf16 v[114:117], v[158:161], v[204:207], v[114:117]
	v_mfma_f32_16x16x32_bf16 v[114:117], v[162:165], v[208:211], v[114:117]
	v_mfma_f32_16x16x32_bf16 v[118:121], v[166:169], v[176:179], v[118:121]
	v_mfma_f32_16x16x32_bf16 v[118:121], v[172:175], v[180:183], v[118:121]
	v_mfma_f32_16x16x32_bf16 v[122:125], v[166:169], v[184:187], v[122:125]
	v_mfma_f32_16x16x32_bf16 v[122:125], v[172:175], v[188:191], v[122:125]
	v_mfma_f32_16x16x32_bf16 v[126:129], v[166:169], v[196:199], v[126:129]
	v_mfma_f32_16x16x32_bf16 v[126:129], v[172:175], v[200:203], v[126:129]
	v_mfma_f32_16x16x32_bf16 v[130:133], v[166:169], v[204:207], v[130:133]
	v_mfma_f32_16x16x32_bf16 v[130:133], v[172:175], v[208:211], v[130:133]
	s_barrier
	s_setprio 0
	ds_read_b128 v[176:179], v136 offset:49152
	ds_read_b128 v[180:183], v136 offset:50176
	ds_read_b128 v[184:187], v136 offset:51200
	ds_read_b128 v[188:191], v136 offset:52224
	ds_read_b128 v[196:199], v136 offset:53248
	ds_read_b128 v[200:203], v136 offset:54272
	ds_read_b128 v[204:207], v136 offset:55296
	ds_read_b128 v[208:211], v136 offset:56320
	s_add_i32 m0, s43, 0x18000
	s_nop 0
	global_load_lds_dwordx4 v134, s[12:13]
	s_nop 0
	s_add_i32 m0, s43, 0x1a000
	s_nop 0
	global_load_lds_dwordx4 v135, s[12:13]
	s_add_u32 s12, s12, s16
	s_addc_u32 s13, s13, 0
	s_add_i32 m0, s43, 0x1c000
	s_nop 0
	global_load_lds_dwordx4 v134, s[12:13]
	s_nop 0
	s_add_i32 m0, s43, 0x1e000
	s_nop 0
	global_load_lds_dwordx4 v135, s[12:13]
	s_nop 0
	s_add_i32 m0, s43, 0x8000
	s_nop 0
	global_load_lds_dwordx4 v134, s[2:3]
	s_nop 0
	s_add_i32 m0, s43, 0xa000
	s_nop 0
	global_load_lds_dwordx4 v135, s[2:3]
	s_waitcnt vmcnt(8)
	s_waitcnt lgkmcnt(0)
	s_setprio 1
	s_barrier
	v_mfma_f32_16x16x32_bf16 v[4:7], v[142:145], v[176:179], v[4:7]
	v_mfma_f32_16x16x32_bf16 v[6:9], v[146:149], v[180:183], v[4:7]
	v_mfma_f32_16x16x32_bf16 v[22:25], v[150:153], v[176:179], v[22:25]
	v_mfma_f32_16x16x32_bf16 v[22:25], v[154:157], v[180:183], v[22:25]
	v_mfma_f32_16x16x32_bf16 v[10:13], v[142:145], v[184:187], v[10:13]
	v_mfma_f32_16x16x32_bf16 v[10:13], v[146:149], v[188:191], v[10:13]
	v_mfma_f32_16x16x32_bf16 v[26:29], v[150:153], v[184:187], v[26:29]
	v_mfma_f32_16x16x32_bf16 v[26:29], v[154:157], v[188:191], v[26:29]
	v_mfma_f32_16x16x32_bf16 v[14:17], v[142:145], v[196:199], v[14:17]
	v_mfma_f32_16x16x32_bf16 v[14:17], v[146:149], v[200:203], v[14:17]
	v_mfma_f32_16x16x32_bf16 v[30:33], v[150:153], v[196:199], v[30:33]
	v_mfma_f32_16x16x32_bf16 v[30:33], v[154:157], v[200:203], v[30:33]
	v_mfma_f32_16x16x32_bf16 v[18:21], v[142:145], v[204:207], v[18:21]
	v_mfma_f32_16x16x32_bf16 v[18:21], v[146:149], v[208:211], v[18:21]
	v_mfma_f32_16x16x32_bf16 v[34:37], v[150:153], v[204:207], v[34:37]
	v_mfma_f32_16x16x32_bf16 v[34:37], v[154:157], v[208:211], v[34:37]
	v_mfma_f32_16x16x32_bf16 v[38:41], v[158:161], v[176:179], v[38:41]
	v_mfma_f32_16x16x32_bf16 v[38:41], v[162:165], v[180:183], v[38:41]
	v_mfma_f32_16x16x32_bf16 v[54:57], v[166:169], v[176:179], v[54:57]
	v_mfma_f32_16x16x32_bf16 v[54:57], v[172:175], v[180:183], v[54:57]
	v_mfma_f32_16x16x32_bf16 v[42:45], v[158:161], v[184:187], v[42:45]
	v_mfma_f32_16x16x32_bf16 v[42:45], v[162:165], v[188:191], v[42:45]
	v_mfma_f32_16x16x32_bf16 v[58:61], v[166:169], v[184:187], v[58:61]
	v_mfma_f32_16x16x32_bf16 v[58:61], v[172:175], v[188:191], v[58:61]
	v_mfma_f32_16x16x32_bf16 v[46:49], v[158:161], v[196:199], v[46:49]
	v_mfma_f32_16x16x32_bf16 v[46:49], v[162:165], v[200:203], v[46:49]
	v_mfma_f32_16x16x32_bf16 v[62:65], v[166:169], v[196:199], v[62:65]
	v_mfma_f32_16x16x32_bf16 v[62:65], v[172:175], v[200:203], v[62:65]
	v_mfma_f32_16x16x32_bf16 v[50:53], v[158:161], v[204:207], v[50:53]
	v_mfma_f32_16x16x32_bf16 v[50:53], v[162:165], v[208:211], v[50:53]
	v_mfma_f32_16x16x32_bf16 v[66:69], v[166:169], v[204:207], v[66:69]
	v_mfma_f32_16x16x32_bf16 v[66:69], v[172:175], v[208:211], v[66:69]
	s_barrier
	s_setprio 0
	s_cmp_ge_u32 s90, s55
	s_cbranch_scc1 .LBB0_848
